# P0 row loop: next trip's row-A x prefetched into spare VGPRs at the start of the row-B half (loop top no longer waits on a fresh load)
# speedup vs baseline: 1.0005x; 1.0001x over previous
.LBB0_23:
	s_or_b64 exec, exec, s[0:1]
	s_movk_i32 s24, 0x4200
	v_cmp_gt_i32_e32 vcc, s24, v42
	v_mbcnt_lo_u32_b32 v185, -1, 0
	s_waitcnt lgkmcnt(0)
	s_barrier
	s_and_saveexec_b64 s[0:1], vcc
	s_cbranch_execz .LBB0_31
	v_readlane_b32 s76, v254, 5
	v_readlane_b32 s77, v254, 6
	v_readlane_b32 s78, v254, 7
	v_readlane_b32 s79, v254, 8
	v_and_b32_e32 v112, 3, v148
	v_lshlrev_b32_e32 v112, 2, v112
	s_nop 4
	global_load_dword v110, v112, s[76:77]
	global_load_dword v111, v112, s[78:79]
	s_mov_b64 s[18:19], 2
	s_mov_b64 s[20:21], 4
	s_mov_b64 s[22:23], 8
	s_mov_b64 s[68:69], 15
	v_lshlrev_b32_e32 v1, 4, v148
	global_load_dwordx4 v[2:5], v1, s[64:65]
	global_load_dwordx4 v[6:9], v1, s[64:65] offset:1024
	global_load_dwordx4 v[10:13], v1, s[64:65] offset:2048
	global_load_dwordx4 v[14:17], v1, s[64:65] offset:3072
	v_mbcnt_hi_u32_b32 v18, -1, v185
	v_and_b32_e32 v19, 64, v18
	v_add_u32_e32 v19, 64, v19
	v_xor_b32_e32 v20, 1, v18
	v_cmp_lt_i32_e32 vcc, v20, v19
	s_lshl_b32 s6, s90, 4
	v_ashrrev_i32_e32 v43, 31, v42
	v_cndmask_b32_e32 v20, v18, v20, vcc
	v_lshlrev_b32_e32 v66, 2, v20
	v_xor_b32_e32 v20, 2, v18
	v_cmp_lt_i32_e32 vcc, v20, v19
	s_ashr_i32 s7, s6, 31
	v_lshlrev_b64 v[50:51], 11, v[42:43]
	v_cndmask_b32_e32 v20, v18, v20, vcc
	v_lshlrev_b32_e32 v67, 2, v20
	v_xor_b32_e32 v20, 4, v18
	v_cmp_lt_i32_e32 vcc, v20, v19
	v_mov_b32_e32 v45, 0
	v_add_u32_e32 v1, s73, v1
	v_cndmask_b32_e32 v20, v18, v20, vcc
	v_lshlrev_b32_e32 v68, 2, v20
	v_xor_b32_e32 v20, 8, v18
	v_cmp_lt_i32_e32 vcc, v20, v19
	v_cmp_eq_u32_e64 s[2:3], 0, v148
	s_lshl_b64 s[8:9], s[6:7], 5
	v_cndmask_b32_e32 v20, v18, v20, vcc
	v_lshlrev_b32_e32 v69, 2, v20
	v_xor_b32_e32 v20, 16, v18
	v_cmp_lt_i32_e32 vcc, v20, v19
	s_lshl_b64 s[10:11], s[6:7], 11
	v_lshlrev_b64 v[52:53], 5, v[42:43]
	v_cndmask_b32_e32 v20, v18, v20, vcc
	v_lshlrev_b32_e32 v70, 2, v20
	v_xor_b32_e32 v20, 32, v18
	v_cmp_lt_i32_e32 vcc, v20, v19
	s_mov_b64 s[12:13], 0
	s_movk_i32 s25, 0x4000
	v_cndmask_b32_e32 v18, v18, v20, vcc
	v_lshlrev_b32_e32 v71, 2, v18
	v_add_u32_e32 v18, s33, v42
	v_ashrrev_i32_e32 v19, 31, v18
	v_lshlrev_b64 v[46:47], 5, v[18:19]
	v_lshlrev_b64 v[48:49], 11, v[18:19]
	v_lshlrev_b32_e32 v18, 3, v148
	v_or_b32_e32 v48, v48, v18
	v_or_b32_e32 v50, v50, v18
	v_mov_b32_e32 v72, s55
	v_mov_b32_e32 v73, s53
	v_lshlrev_b32_e32 v44, 4, v148
	v_mov_b32_e32 v74, 0x358637bd
	s_mov_b32 s28, 0x800000
	s_mov_b32 s29, 0x276e000
	s_mov_b32 s30, 0xbfb8aa3b
	s_mov_b32 s31, 0xb2a5705f
	s_mov_b32 s34, 0x42ce8ed0
	s_mov_b32 s35, 0xc2b17218
	s_mov_b32 s64, 0x7f800000
	s_mov_b32 s65, 0x3f2aaaab
	v_mov_b32_e32 v75, 0x3ecc95a3
	s_mov_b32 s66, 0x3f317218
	s_mov_b32 s67, 0x33800000
	s_movk_i32 s84, 0x41ff
	v_mov_b32_e32 v76, 0x7f800000
	v_add_u32_e32 v134, 0xffffc000, v42
	v_cmp_gt_i32_e32 vcc, s25, v42
	v_mov_b32_e32 v136, s54
	v_mov_b32_e32 v137, s52
	v_mov_b32_e32 v135, 0
	v_cndmask_b32_e32 v134, v134, v42, vcc
	v_cndmask_b32_e32 v139, v72, v73, vcc
	v_cndmask_b32_e32 v138, v136, v137, vcc
	v_lshlrev_b64 v[134:135], 12, v[134:135]
	v_lshl_add_u64 v[134:135], v[138:139], 0, v[134:135]
	v_lshl_add_u64 v[134:135], v[134:135], 0, v[44:45]
	global_load_dwordx4 v[116:119], v[134:135], off
	global_load_dwordx4 v[120:123], v[134:135], off offset:1024
	global_load_dwordx4 v[124:127], v[134:135], off offset:3072
	global_load_dwordx4 v[128:131], v[134:135], off offset:2048
	s_waitcnt vmcnt(0)
	s_branch .LBB0_26
.Lp0_nob:
	s_waitcnt vmcnt(0)
.LBB0_25:
	s_or_b64 exec, exec, s[26:27]
	v_lshl_add_u64 v[42:43], v[42:43], 0, s[6:7]
	v_cmp_lt_i32_e32 vcc, s84, v42
	v_lshl_add_u64 v[46:47], v[46:47], 0, s[8:9]
	v_lshl_add_u64 v[48:49], v[48:49], 0, s[10:11]
	v_lshl_add_u64 v[50:51], v[50:51], 0, s[10:11]
	s_or_b64 s[12:13], vcc, s[12:13]
	v_lshl_add_u64 v[52:53], v[52:53], 0, s[8:9]
	s_andn2_b64 exec, exec, s[12:13]
	s_cbranch_execz .LBB0_31
.LBB0_26:
	v_add_u32_e32 v18, 0xffffc000, v42
	v_cmp_gt_i32_e32 vcc, s25, v42
	v_mov_b32_e32 v29, s54
	v_mov_b32_e32 v32, s52
	v_cndmask_b32_e32 v19, 0, v43, vcc
	v_cndmask_b32_e32 v18, v18, v42, vcc
	s_waitcnt lgkmcnt(0)
	v_cndmask_b32_e32 v21, v72, v73, vcc
	v_cndmask_b32_e32 v20, v29, v32, vcc
	v_lshlrev_b64 v[18:19], 12, v[18:19]
	v_lshl_add_u64 v[18:19], v[20:21], 0, v[18:19]
	v_lshl_add_u64 v[18:19], v[18:19], 0, v[44:45]
	s_waitcnt vmcnt(2)
	v_mov_b32_e32 v56, v116
	v_mov_b32_e32 v57, v117
	v_mov_b32_e32 v58, v118
	v_mov_b32_e32 v59, v119
	v_mov_b32_e32 v60, v120
	v_mov_b32_e32 v61, v121
	v_mov_b32_e32 v62, v122
	v_mov_b32_e32 v63, v123
	v_mov_b32_e32 v34, v124
	v_mov_b32_e32 v35, v125
	v_mov_b32_e32 v36, v126
	v_mov_b32_e32 v37, v127
	v_mov_b32_e32 v38, v128
	v_mov_b32_e32 v39, v129
	v_mov_b32_e32 v40, v130
	v_mov_b32_e32 v41, v131
	v_pk_mul_f32 v[18:19], v[58:59], v[58:59]
	v_pk_mul_f32 v[20:21], v[56:57], v[56:57]
	v_pk_mul_f32 v[22:23], v[62:63], v[62:63]
	v_pk_mul_f32 v[24:25], v[60:61], v[60:61]
	v_pk_mov_b32 v[30:31], v[20:21], v[18:19] op_sel:[1,0]
	v_mov_b32_e32 v21, v19
	v_pk_mov_b32 v[18:19], v[24:25], v[22:23] op_sel:[1,0]
	v_mov_b32_e32 v25, v23
	v_mul_f32_e32 v26, v39, v39
	v_mul_f32_e32 v28, v41, v41
	v_pk_add_f32 v[20:21], v[30:31], v[20:21]
	v_pk_add_f32 v[18:19], v[18:19], v[24:25]
	v_mul_f32_e32 v33, v34, v34
	v_mul_f32_e32 v54, v35, v35
	v_mul_f32_e32 v55, v36, v36
	v_mul_f32_e32 v64, v37, v37
	v_pk_fma_f32 v[22:23], v[38:39], v[38:39], v[26:27] op_sel_hi:[1,1,0]
	v_pk_fma_f32 v[26:27], v[40:41], v[40:41], v[28:29] op_sel_hi:[1,1,0]
	v_pk_add_f32 v[20:21], v[20:21], v[20:21] op_sel:[0,1] op_sel_hi:[1,0]
	v_pk_add_f32 v[18:19], v[18:19], v[18:19] op_sel:[0,1] op_sel_hi:[1,0]
	v_mov_b32_e32 v23, v55
	v_mov_b32_e32 v27, v64
	v_mov_b32_e32 v21, v33
	v_mov_b32_e32 v19, v54
	v_pk_add_f32 v[22:23], v[22:23], v[26:27]
	v_pk_add_f32 v[18:19], v[20:21], v[18:19]
	v_add_u32_e32 v20, s33, v42
	v_pk_add_f32 v[18:19], v[18:19], v[22:23]
	v_cmp_gt_i32_e64 s[4:5], s24, v20
	v_add_f32_e32 v18, v18, v19
	ds_bpermute_b32 v19, v66, v18
	v_cndmask_b32_e64 v20, v42, v20, s[4:5]
	v_add_u32_e32 v25, 0xffffc000, v20
	v_mov_b32_e32 v21, s55
	v_mov_b32_e32 v24, s53
	s_waitcnt lgkmcnt(0)
	v_add_f32_e32 v18, v18, v19
	ds_bpermute_b32 v19, v67, v18
	s_waitcnt lgkmcnt(0)
	v_add_f32_e32 v22, v18, v19
	ds_bpermute_b32 v23, v68, v22
	v_lshl_add_u64 v[18:19], s[74:75], 0, v[50:51]
	v_add_co_u32_e32 v54, vcc, s29, v18
	v_ashrrev_i32_e32 v18, 31, v20
	s_waitcnt lgkmcnt(0)
	v_add_f32_e32 v22, v22, v23
	ds_bpermute_b32 v23, v69, v22
	v_addc_co_u32_e32 v55, vcc, 0, v19, vcc
	v_cmp_gt_i32_e32 vcc, s25, v20
	s_waitcnt lgkmcnt(0)
	v_add_f32_e32 v22, v22, v23
	ds_bpermute_b32 v23, v70, v22
	v_cndmask_b32_e32 v19, 0, v18, vcc
	v_cndmask_b32_e32 v18, v25, v20, vcc
	v_cndmask_b32_e32 v21, v21, v24, vcc
	v_cndmask_b32_e32 v20, v29, v32, vcc
	s_waitcnt lgkmcnt(0)
	v_add_f32_e32 v22, v22, v23
	ds_bpermute_b32 v23, v71, v22
	v_lshlrev_b64 v[18:19], 12, v[18:19]
	v_lshl_add_u64 v[18:19], v[20:21], 0, v[18:19]
	v_lshl_add_u64 v[18:19], v[18:19], 0, v[44:45]
	s_waitcnt lgkmcnt(0)
	v_add_f32_e32 v20, v22, v23
	v_fmamk_f32 v20, v20, 0x3a800000, v74
	v_mul_f32_e32 v21, 0x4b800000, v20
	v_cmp_gt_f32_e32 vcc, s28, v20
	s_nop 1
	v_cndmask_b32_e32 v20, v20, v21, vcc
	v_rsq_f32_e32 v64, v20
	global_load_dwordx4 v[30:33], v[18:19], off
	global_load_dwordx4 v[26:29], v[18:19], off offset:1024
	global_load_dwordx4 v[22:25], v[18:19], off offset:2048
	s_nop 0
	global_load_dwordx4 v[18:21], v[18:19], off offset:3072
	v_mul_f32_e32 v65, 0x45800000, v64
	v_cndmask_b32_e32 v64, v64, v65, vcc
	v_pk_mul_f32 v[56:57], v[56:57], v[64:65] op_sel_hi:[1,0]
	v_pk_mul_f32 v[58:59], v[58:59], v[64:65] op_sel_hi:[1,0]
	v_pk_mul_f32 v[38:39], v[38:39], v[64:65] op_sel_hi:[1,0]
	v_pk_mul_f32 v[34:35], v[34:35], v[64:65] op_sel_hi:[1,0]
	v_pk_mul_f32 v[60:61], v[60:61], v[64:65] op_sel_hi:[1,0]
	v_pk_mul_f32 v[78:79], v[62:63], v[64:65] op_sel_hi:[1,0]
	v_pk_mul_f32 v[40:41], v[40:41], v[64:65] op_sel_hi:[1,0]
	v_pk_mul_f32 v[36:37], v[36:37], v[64:65] op_sel_hi:[1,0]
	v_pk_mul_f32 v[62:63], v[4:5], v[58:59]
	v_pk_mul_f32 v[64:65], v[2:3], v[56:57]
	v_pk_mul_f32 v[56:57], v[10:11], v[38:39]
	v_pk_mul_f32 v[38:39], v[14:15], v[34:35]
	v_cvt_pk_bf16_f32 v34, v64, v65
	v_cvt_pk_bf16_f32 v35, v62, v63
	v_pk_mul_f32 v[58:59], v[8:9], v[78:79]
	v_pk_mul_f32 v[60:61], v[6:7], v[60:61]
	global_store_dwordx2 v[54:55], v[34:35], off
	v_cvt_pk_bf16_f32 v34, v60, v61
	v_cvt_pk_bf16_f32 v35, v58, v59
	v_pk_mul_f32 v[40:41], v[12:13], v[40:41]
	global_store_dwordx2 v[54:55], v[34:35], off offset:512
	v_cvt_pk_bf16_f32 v34, v56, v57
	v_cvt_pk_bf16_f32 v35, v40, v41
	v_pk_mul_f32 v[36:37], v[16:17], v[36:37]
	global_store_dwordx2 v[54:55], v[34:35], off offset:1024
	v_cvt_pk_bf16_f32 v34, v38, v39
	v_cvt_pk_bf16_f32 v35, v36, v37
	ds_read_b128 v[78:81], v1
	ds_read_b128 v[82:85], v1 offset:1024
	ds_read_b128 v[86:89], v1 offset:2048
	ds_read_b128 v[90:93], v1 offset:3072
	ds_read_b128 v[94:97], v1 offset:4096
	ds_read_b128 v[98:101], v1 offset:5120
	ds_read_b128 v[102:105], v1 offset:6144
	ds_read_b128 v[106:109], v1 offset:7168
	s_waitcnt lgkmcnt(7)
	v_mul_f32_e32 v77, v65, v79
	v_mul_f32_e32 v79, v63, v81
	s_waitcnt lgkmcnt(6)
	v_mul_f32_e32 v81, v61, v83
	v_mul_f32_e32 v83, v59, v85
	v_fmac_f32_e32 v77, v64, v78
	v_fmac_f32_e32 v79, v62, v80
	s_waitcnt lgkmcnt(5)
	v_mul_f32_e32 v85, v57, v87
	v_mul_f32_e32 v87, v41, v89
	v_fmac_f32_e32 v81, v60, v82
	v_fmac_f32_e32 v83, v58, v84
	v_add_f32_e32 v77, v77, v79
	s_waitcnt lgkmcnt(4)
	v_mul_f32_e32 v89, v39, v91
	v_mul_f32_e32 v91, v37, v93
	v_fmac_f32_e32 v85, v56, v86
	v_fmac_f32_e32 v87, v40, v88
	v_add_f32_e32 v78, v81, v83
	v_add_f32_e32 v77, 0, v77
	v_fmac_f32_e32 v89, v38, v90
	v_fmac_f32_e32 v91, v36, v92
	v_add_f32_e32 v79, v85, v87
	v_add_f32_e32 v77, v77, v78
	s_waitcnt lgkmcnt(3)
	v_mul_f32_e32 v93, v65, v95
	v_mul_f32_e32 v95, v63, v97
	v_add_f32_e32 v80, v89, v91
	v_add_f32_e32 v77, v77, v79
	s_waitcnt lgkmcnt(2)
	v_mul_f32_e32 v97, v61, v99
	v_mul_f32_e32 v99, v59, v101
	v_fmac_f32_e32 v93, v64, v94
	v_fmac_f32_e32 v95, v62, v96
	v_add_f32_e32 v77, v77, v80
	v_fmac_f32_e32 v97, v60, v98
	v_fmac_f32_e32 v99, v58, v100
	ds_bpermute_b32 v78, v66, v77
	v_add_f32_e32 v79, v93, v95
	v_add_f32_e32 v80, v97, v99
	v_add_f32_e32 v79, 0, v79
	s_waitcnt lgkmcnt(2)
	v_mul_f32_e32 v101, v57, v103
	v_add_f32_e32 v79, v79, v80
	v_mul_f32_e32 v80, v41, v105
	v_fmac_f32_e32 v101, v56, v102
	v_fmac_f32_e32 v80, v40, v104
	v_add_f32_e32 v80, v101, v80
	s_waitcnt lgkmcnt(0)
	v_add_f32_e32 v77, v77, v78
	v_add_f32_e32 v79, v79, v80
	v_mul_f32_e32 v80, v39, v107
	v_mul_f32_e32 v81, v37, v109
	ds_bpermute_b32 v78, v67, v77
	v_fmac_f32_e32 v80, v38, v106
	v_fmac_f32_e32 v81, v36, v108
	v_add_f32_e32 v80, v80, v81
	v_add_f32_e32 v79, v79, v80
	ds_bpermute_b32 v80, v66, v79
	s_waitcnt lgkmcnt(1)
	v_add_f32_e32 v77, v77, v78
	ds_bpermute_b32 v78, v68, v77
	global_store_dwordx2 v[54:55], v[34:35], off offset:1536
	s_waitcnt lgkmcnt(1)
	v_add_f32_e32 v82, v79, v80
	ds_bpermute_b32 v83, v67, v82
	s_waitcnt lgkmcnt(1)
	v_add_f32_e32 v77, v77, v78
	ds_read_b128 v[78:81], v1 offset:8192
	ds_bpermute_b32 v86, v69, v77
	s_waitcnt lgkmcnt(2)
	v_add_f32_e32 v87, v82, v83
	ds_read_b128 v[82:85], v1 offset:9216
	s_waitcnt lgkmcnt(2)
	v_mul_f32_e32 v79, v65, v79
	v_fmac_f32_e32 v79, v64, v78
	v_mul_f32_e32 v78, v63, v81
	v_fmac_f32_e32 v78, v62, v80
	v_add_f32_e32 v78, v79, v78
	s_waitcnt lgkmcnt(0)
	v_mul_f32_e32 v83, v61, v83
	v_add_f32_e32 v89, 0, v78
	v_fmac_f32_e32 v83, v60, v82
	v_mul_f32_e32 v82, v59, v85
	ds_read_b128 v[78:81], v1 offset:10240
	v_fmac_f32_e32 v82, v58, v84
	v_add_f32_e32 v82, v83, v82
	v_add_f32_e32 v89, v89, v82
	ds_read_b128 v[82:85], v1 offset:11264
	s_waitcnt lgkmcnt(1)
	v_mul_f32_e32 v79, v57, v79
	v_fmac_f32_e32 v79, v56, v78
	v_mul_f32_e32 v78, v41, v81
	v_fmac_f32_e32 v78, v40, v80
	v_add_f32_e32 v78, v79, v78
	s_waitcnt lgkmcnt(0)
	v_mul_f32_e32 v79, v39, v83
	v_mul_f32_e32 v80, v37, v85
	v_fmac_f32_e32 v79, v38, v82
	v_fmac_f32_e32 v80, v36, v84
	v_add_f32_e32 v78, v89, v78
	v_add_f32_e32 v79, v79, v80
	v_add_f32_e32 v78, v78, v79
	ds_bpermute_b32 v88, v68, v87
	ds_bpermute_b32 v79, v66, v78
	v_add_f32_e32 v77, v77, v86
	ds_bpermute_b32 v80, v70, v77
	s_waitcnt lgkmcnt(2)
	v_add_f32_e32 v84, v87, v88
	s_waitcnt lgkmcnt(1)
	v_add_f32_e32 v79, v78, v79
	ds_bpermute_b32 v85, v69, v84
	ds_bpermute_b32 v86, v67, v79
	s_waitcnt lgkmcnt(2)
	v_add_f32_e32 v77, v77, v80
	ds_read_b128 v[80:83], v1 offset:12288
	ds_bpermute_b32 v78, v71, v77
	s_waitcnt lgkmcnt(3)
	v_add_f32_e32 v88, v84, v85
	s_waitcnt lgkmcnt(2)
	v_add_f32_e32 v79, v79, v86
	ds_read_b128 v[84:87], v1 offset:13312
	s_waitcnt lgkmcnt(2)
	v_mul_f32_e32 v81, v65, v81
	v_fmac_f32_e32 v81, v64, v80
	v_mul_f32_e32 v80, v63, v83
	v_fmac_f32_e32 v80, v62, v82
	v_add_f32_e32 v80, v81, v80
	s_waitcnt lgkmcnt(0)
	v_mul_f32_e32 v85, v61, v85
	v_add_f32_e32 v90, 0, v80
	v_fmac_f32_e32 v85, v60, v84
	v_mul_f32_e32 v84, v59, v87
	ds_read_b128 v[80:83], v1 offset:14336
	v_fmac_f32_e32 v84, v58, v86
	v_add_f32_e32 v84, v85, v84
	v_add_f32_e32 v90, v90, v84
	ds_read_b128 v[84:87], v1 offset:15360
	s_waitcnt lgkmcnt(1)
	v_mul_f32_e32 v81, v57, v81
	v_fmac_f32_e32 v81, v56, v80
	v_mul_f32_e32 v80, v41, v83
	v_fmac_f32_e32 v80, v40, v82
	v_add_f32_e32 v80, v81, v80
	s_waitcnt lgkmcnt(0)
	v_mul_f32_e32 v85, v39, v85
	v_add_f32_e32 v90, v90, v80
	v_fmac_f32_e32 v85, v38, v84
	v_mul_f32_e32 v84, v37, v87
	ds_read_b128 v[80:83], v1 offset:16384
	v_fmac_f32_e32 v84, v36, v86
	v_add_f32_e32 v84, v85, v84
	v_add_f32_e32 v90, v90, v84
	ds_read_b128 v[84:87], v1 offset:17408
	s_waitcnt lgkmcnt(1)
	v_mul_f32_e32 v81, v65, v81
	v_fmac_f32_e32 v81, v64, v80
	v_mul_f32_e32 v80, v63, v83
	v_fmac_f32_e32 v80, v62, v82
	v_add_f32_e32 v80, v81, v80
	s_waitcnt lgkmcnt(0)
	v_mul_f32_e32 v85, v61, v85
	v_add_f32_e32 v92, 0, v80
	v_fmac_f32_e32 v85, v60, v84
	v_mul_f32_e32 v84, v59, v87
	ds_read_b128 v[80:83], v1 offset:18432
	v_fmac_f32_e32 v84, v58, v86
	v_add_f32_e32 v84, v85, v84
	v_add_f32_e32 v92, v92, v84
	ds_read_b128 v[84:87], v1 offset:19456
	s_waitcnt lgkmcnt(1)
	v_mul_f32_e32 v81, v57, v81
	v_fmac_f32_e32 v81, v56, v80
	v_mul_f32_e32 v80, v41, v83
	ds_bpermute_b32 v91, v66, v90
	v_fmac_f32_e32 v80, v40, v82
	v_add_f32_e32 v80, v81, v80
	s_waitcnt lgkmcnt(1)
	v_mul_f32_e32 v81, v39, v85
	v_mul_f32_e32 v82, v37, v87
	v_fmac_f32_e32 v81, v38, v84
	v_fmac_f32_e32 v82, v36, v86
	v_add_f32_e32 v80, v92, v80
	v_add_f32_e32 v81, v81, v82
	v_add_f32_e32 v80, v80, v81
	ds_bpermute_b32 v81, v66, v80
	s_waitcnt lgkmcnt(1)
	v_add_f32_e32 v83, v90, v91
	ds_bpermute_b32 v84, v67, v83
	ds_bpermute_b32 v89, v68, v79
	ds_bpermute_b32 v82, v70, v88
	s_waitcnt lgkmcnt(3)
	v_add_f32_e32 v80, v80, v81
	ds_bpermute_b32 v81, v67, v80
	s_waitcnt lgkmcnt(3)
	v_add_f32_e32 v83, v83, v84
	ds_bpermute_b32 v84, v68, v83
	s_waitcnt lgkmcnt(3)
	v_add_f32_e32 v85, v79, v89
	ds_bpermute_b32 v86, v69, v85
	s_waitcnt lgkmcnt(2)
	v_add_f32_e32 v80, v80, v81
	ds_bpermute_b32 v81, v68, v80
	s_waitcnt lgkmcnt(2)
	v_add_f32_e32 v83, v83, v84
	ds_bpermute_b32 v84, v69, v83
	s_waitcnt lgkmcnt(2)
	v_add_f32_e32 v85, v85, v86
	ds_bpermute_b32 v86, v70, v85
	s_waitcnt lgkmcnt(2)
	v_add_f32_e32 v81, v80, v81
	ds_bpermute_b32 v87, v69, v81
	s_waitcnt lgkmcnt(2)
	v_add_f32_e32 v84, v83, v84
	v_add_f32_e32 v79, v88, v82
	ds_bpermute_b32 v88, v70, v84
	s_waitcnt lgkmcnt(2)
	v_add_f32_e32 v80, v85, v86
	s_waitcnt lgkmcnt(1)
	v_add_f32_e32 v85, v81, v87
	ds_bpermute_b32 v87, v70, v85
	ds_read_b128 v[92:95], v1 offset:21504
	s_waitcnt lgkmcnt(2)
	v_add_f32_e32 v81, v84, v88
	ds_read_b128 v[88:91], v1 offset:20480
	ds_bpermute_b32 v82, v71, v79
	s_waitcnt lgkmcnt(3)
	v_add_f32_e32 v84, v85, v87
	s_waitcnt lgkmcnt(2)
	v_mul_f32_e32 v93, v61, v93
	v_fmac_f32_e32 v93, v60, v92
	s_waitcnt lgkmcnt(1)
	v_mul_f32_e32 v87, v65, v89
	v_fmac_f32_e32 v87, v64, v88
	v_mul_f32_e32 v88, v63, v91
	v_fmac_f32_e32 v88, v62, v90
	v_mul_f32_e32 v92, v59, v95
	v_add_f32_e32 v87, v87, v88
	ds_read_b128 v[88:91], v1 offset:22528
	v_fmac_f32_e32 v92, v58, v94
	v_add_f32_e32 v87, 0, v87
	v_add_f32_e32 v92, v93, v92
	v_add_f32_e32 v87, v87, v92
	ds_read_b128 v[92:95], v1 offset:23552
	s_waitcnt lgkmcnt(1)
	v_mul_f32_e32 v89, v57, v89
	v_fmac_f32_e32 v89, v56, v88
	v_mul_f32_e32 v88, v41, v91
	v_fmac_f32_e32 v88, v40, v90
	s_waitcnt lgkmcnt(0)
	v_mul_f32_e32 v93, v39, v93
	v_add_f32_e32 v88, v89, v88
	v_fmac_f32_e32 v93, v38, v92
	v_mul_f32_e32 v92, v37, v95
	v_add_f32_e32 v87, v87, v88
	v_fmac_f32_e32 v92, v36, v94
	ds_read_b128 v[88:91], v1 offset:24576
	v_add_f32_e32 v92, v93, v92
	v_add_f32_e32 v87, v87, v92
	ds_read_b128 v[92:95], v1 offset:25600
	ds_bpermute_b32 v96, v66, v87
	s_waitcnt lgkmcnt(2)
	v_mul_f32_e32 v89, v65, v89
	v_fmac_f32_e32 v89, v64, v88
	v_mul_f32_e32 v88, v63, v91
	v_fmac_f32_e32 v88, v62, v90
	s_waitcnt lgkmcnt(1)
	v_mul_f32_e32 v93, v61, v93
	v_add_f32_e32 v88, v89, v88
	v_fmac_f32_e32 v93, v60, v92
	v_mul_f32_e32 v92, v59, v95
	v_add_f32_e32 v97, 0, v88
	ds_read_b128 v[88:91], v1 offset:26624
	v_fmac_f32_e32 v92, v58, v94
	v_add_f32_e32 v92, v93, v92
	v_add_f32_e32 v97, v97, v92
	ds_read_b128 v[92:95], v1 offset:27648
	s_waitcnt lgkmcnt(1)
	v_mul_f32_e32 v89, v57, v89
	v_fmac_f32_e32 v89, v56, v88
	v_mul_f32_e32 v88, v41, v91
	v_fmac_f32_e32 v88, v40, v90
	s_waitcnt lgkmcnt(0)
	v_mul_f32_e32 v93, v39, v93
	v_add_f32_e32 v88, v89, v88
	v_fmac_f32_e32 v93, v38, v92
	v_mul_f32_e32 v92, v37, v95
	v_add_f32_e32 v97, v97, v88
	v_fmac_f32_e32 v92, v36, v94
	ds_read_b128 v[88:91], v1 offset:28672
	v_add_f32_e32 v92, v93, v92
	v_add_f32_e32 v97, v97, v92
	ds_read_b128 v[92:95], v1 offset:29696
	ds_bpermute_b32 v98, v66, v97
	s_waitcnt lgkmcnt(2)
	v_mul_f32_e32 v65, v65, v89
	v_mul_f32_e32 v63, v63, v91
	v_fmac_f32_e32 v65, v64, v88
	v_fmac_f32_e32 v63, v62, v90
	v_add_f32_e32 v62, v65, v63
	s_waitcnt lgkmcnt(1)
	v_mul_f32_e32 v65, v61, v93
	v_add_f32_e32 v64, 0, v62
	v_fmac_f32_e32 v65, v60, v92
	ds_read_b128 v[60:63], v1 offset:30720
	ds_read_b128 v[88:91], v1 offset:31744
	v_mul_f32_e32 v59, v59, v95
	v_fmac_f32_e32 v59, v58, v94
	v_add_f32_e32 v58, v65, v59
	s_waitcnt lgkmcnt(1)
	v_mul_f32_e32 v57, v57, v61
	v_mul_f32_e32 v41, v41, v63
	v_fmac_f32_e32 v57, v56, v60
	v_fmac_f32_e32 v41, v40, v62
	s_waitcnt lgkmcnt(0)
	v_mul_f32_e32 v39, v39, v89
	v_mul_f32_e32 v37, v37, v91
	v_add_f32_e32 v58, v64, v58
	v_add_f32_e32 v40, v57, v41
	v_fmac_f32_e32 v39, v38, v88
	v_fmac_f32_e32 v37, v36, v90
	v_add_f32_e32 v40, v58, v40
	v_add_f32_e32 v36, v39, v37
	v_add_f32_e32 v36, v40, v36
	ds_bpermute_b32 v37, v66, v36
	v_add_f32_e32 v38, v87, v96
	v_add_f32_e32 v40, v97, v98
	ds_bpermute_b32 v39, v67, v38
	ds_bpermute_b32 v41, v67, v40
	s_waitcnt lgkmcnt(2)
	v_add_f32_e32 v36, v36, v37
	ds_bpermute_b32 v37, v67, v36
	ds_bpermute_b32 v83, v71, v80
	s_waitcnt lgkmcnt(3)
	v_add_f32_e32 v38, v38, v39
	s_waitcnt lgkmcnt(2)
	v_add_f32_e32 v40, v40, v41
	ds_bpermute_b32 v39, v68, v38
	s_waitcnt lgkmcnt(2)
	v_add_f32_e32 v36, v36, v37
	ds_bpermute_b32 v41, v68, v40
	ds_bpermute_b32 v37, v68, v36
	ds_bpermute_b32 v86, v71, v81
	s_waitcnt lgkmcnt(3)
	v_add_f32_e32 v38, v38, v39
	ds_bpermute_b32 v39, v69, v38
	s_waitcnt lgkmcnt(3)
	v_add_f32_e32 v40, v40, v41
	s_waitcnt lgkmcnt(2)
	v_add_f32_e32 v36, v36, v37
	ds_bpermute_b32 v41, v69, v40
	ds_bpermute_b32 v37, v69, v36
	s_waitcnt lgkmcnt(2)
	v_add_f32_e32 v38, v38, v39
	ds_bpermute_b32 v39, v70, v38
	ds_bpermute_b32 v85, v71, v84
	s_waitcnt lgkmcnt(3)
	v_add_f32_e32 v56, v40, v41
	s_waitcnt lgkmcnt(2)
	v_add_f32_e32 v36, v36, v37
	ds_bpermute_b32 v57, v70, v56
	ds_bpermute_b32 v37, v70, v36
	s_waitcnt lgkmcnt(3)
	v_add_f32_e32 v40, v38, v39
	ds_bpermute_b32 v41, v71, v40
	s_waitcnt lgkmcnt(2)
	v_add_f32_e32 v38, v56, v57
	s_waitcnt lgkmcnt(1)
	v_add_f32_e32 v36, v36, v37
	ds_bpermute_b32 v39, v71, v38
	ds_bpermute_b32 v37, v71, v36
	s_and_saveexec_b64 s[26:27], s[68:69]
	s_waitcnt vmcnt(4)
	s_cbranch_execz .LBB0_28
	v_lshl_add_u64 v[34:35], s[74:75], 0, v[52:53]
	v_add_f32_e32 v55, v77, v78
	v_add_co_u32_e32 v34, vcc, 0x26a8000, v34
	s_nop 0
	v_addc_co_u32_e32 v35, vcc, 0, v35, vcc
	s_waitcnt lgkmcnt(2)
	v_add_f32_e32 v40, v40, v41
	s_waitcnt lgkmcnt(1)
	v_add_f32_e32 v38, v38, v39
	s_waitcnt lgkmcnt(0)
	v_add_f32_e32 v36, v36, v37
	v_add_f32_e32 v56, v79, v82
	v_add_f32_e32 v57, v80, v83
	v_add_f32_e32 v58, v81, v86
	v_cndmask_b32_e64 v55, v55, v56, s[18:19]
	v_cndmask_b32_e64 v55, v55, v57, s[20:21]
	v_cndmask_b32_e64 v55, v55, v58, s[22:23]
	v_add_f32_e32 v54, v110, v55
	v_add_co_u32_e32 v34, vcc, v112, v34
	s_nop 1
	v_addc_co_u32_e32 v35, vcc, 0, v35, vcc
	global_store_dword v[34:35], v54, off
	v_add_f32_e32 v55, v84, v85
	v_cndmask_b32_e64 v55, v55, v40, s[18:19]
	v_cndmask_b32_e64 v55, v55, v38, s[20:21]
	v_cndmask_b32_e64 v55, v55, v36, s[22:23]
	v_add_f32_e32 v54, v111, v55
	s_and_b64 vcc, exec, s[4:5]
	s_cbranch_scc0 .Lp0_fnow
	v_mov_b32_e32 v113, v54
	v_mov_b32_e32 v114, v34
	v_mov_b32_e32 v115, v35
	s_branch .LBB0_28

.LBB0_28:
	s_or_b64 exec, exec, s[26:27]
	v_add_u32_e32 v132, s6, v42
	v_cmp_gt_i32_e32 vcc, s24, v132
	s_and_saveexec_b64 s[36:37], vcc
	v_add_u32_e32 v134, 0xffffc000, v132
	v_cmp_gt_i32_e32 vcc, s25, v132
	v_mov_b32_e32 v136, s54
	v_mov_b32_e32 v137, s52
	v_mov_b32_e32 v135, 0
	v_cndmask_b32_e32 v134, v134, v132, vcc
	v_cndmask_b32_e32 v139, v72, v73, vcc
	v_cndmask_b32_e32 v138, v136, v137, vcc
	v_lshlrev_b64 v[134:135], 12, v[134:135]
	v_lshl_add_u64 v[134:135], v[138:139], 0, v[134:135]
	v_lshl_add_u64 v[134:135], v[134:135], 0, v[44:45]
	global_load_dwordx4 v[116:119], v[134:135], off
	global_load_dwordx4 v[120:123], v[134:135], off offset:1024
	global_load_dwordx4 v[124:127], v[134:135], off offset:3072
	global_load_dwordx4 v[128:131], v[134:135], off offset:2048
	s_mov_b64 exec, s[36:37]
	s_and_saveexec_b64 s[26:27], s[4:5]
	s_cbranch_execz .Lp0_nob
	v_pk_mul_f32 v[34:35], v[32:33], v[32:33]
	s_waitcnt lgkmcnt(0)
	v_pk_mul_f32 v[36:37], v[30:31], v[30:31]
	s_nop 0
	v_pk_mov_b32 v[38:39], v[36:37], v[34:35] op_sel:[1,0]
	v_mov_b32_e32 v37, v35
	v_pk_add_f32 v[34:35], v[38:39], v[36:37]
	v_pk_mul_f32 v[36:37], v[28:29], v[28:29]
	v_pk_mul_f32 v[38:39], v[26:27], v[26:27]
	v_pk_add_f32 v[34:35], v[34:35], v[34:35] op_sel:[0,1] op_sel_hi:[1,0]
	v_pk_mov_b32 v[40:41], v[38:39], v[36:37] op_sel:[1,0]
	v_mov_b32_e32 v39, v37
	v_pk_add_f32 v[36:37], v[40:41], v[38:39]
	v_mul_f32_e32 v38, v18, v18
	v_mul_f32_e32 v39, v19, v19
	v_pk_add_f32 v[36:37], v[36:37], v[36:37] op_sel:[0,1] op_sel_hi:[1,0]
	v_mov_b32_e32 v35, v38
	v_mov_b32_e32 v37, v39
	v_pk_add_f32 v[34:35], v[34:35], v[36:37]
	v_mul_f32_e32 v36, v23, v23
	v_mul_f32_e32 v38, v25, v25
	v_mul_f32_e32 v40, v20, v20
	v_mul_f32_e32 v41, v21, v21
	v_pk_fma_f32 v[36:37], v[22:23], v[22:23], v[36:37] op_sel_hi:[1,1,0]
	v_pk_fma_f32 v[38:39], v[24:25], v[24:25], v[38:39] op_sel_hi:[1,1,0]
	v_mov_b32_e32 v37, v40
	v_mov_b32_e32 v39, v41
	v_pk_add_f32 v[36:37], v[36:37], v[38:39]
	s_nop 0
	v_pk_add_f32 v[34:35], v[34:35], v[36:37]
	v_lshl_add_u64 v[36:37], s[74:75], 0, v[48:49]
	v_add_f32_e32 v34, v34, v35
	ds_bpermute_b32 v35, v66, v34
	s_waitcnt lgkmcnt(0)
	v_add_f32_e32 v34, v34, v35
	ds_bpermute_b32 v35, v67, v34
	s_waitcnt lgkmcnt(0)
	v_add_f32_e32 v34, v34, v35
	ds_bpermute_b32 v35, v68, v34
	s_waitcnt lgkmcnt(0)
	v_add_f32_e32 v34, v34, v35
	ds_bpermute_b32 v35, v69, v34
	s_waitcnt lgkmcnt(0)
	v_add_f32_e32 v34, v34, v35
	ds_bpermute_b32 v35, v70, v34
	s_waitcnt lgkmcnt(0)
	v_add_f32_e32 v34, v34, v35
	ds_bpermute_b32 v35, v71, v34
	s_waitcnt lgkmcnt(0)
	v_add_f32_e32 v34, v34, v35
	v_fmamk_f32 v34, v34, 0x3a800000, v74
	v_mul_f32_e32 v35, 0x4b800000, v34
	v_cmp_gt_f32_e32 vcc, s28, v34
	s_nop 1
	v_cndmask_b32_e32 v34, v34, v35, vcc
	v_rsq_f32_e32 v34, v34
	s_nop 0
	v_mul_f32_e32 v35, 0x45800000, v34
	v_cndmask_b32_e32 v38, v34, v35, vcc
	v_pk_mul_f32 v[30:31], v[30:31], v[38:39] op_sel_hi:[1,0]
	v_pk_mul_f32 v[32:33], v[32:33], v[38:39] op_sel_hi:[1,0]
	v_pk_mul_f32 v[34:35], v[2:3], v[30:31]
	v_add_co_u32_e32 v30, vcc, s29, v36
	v_pk_mul_f32 v[32:33], v[4:5], v[32:33]
	s_nop 0
	v_addc_co_u32_e32 v31, vcc, 0, v37, vcc
	v_pk_mul_f32 v[36:37], v[26:27], v[38:39] op_sel_hi:[1,0]
	v_pk_mul_f32 v[26:27], v[28:29], v[38:39] op_sel_hi:[1,0]
	v_cvt_pk_bf16_f32 v40, v34, v35
	v_cvt_pk_bf16_f32 v41, v32, v33
	global_store_dwordx2 v[30:31], v[40:41], off
	v_pk_mul_f32 v[26:27], v[8:9], v[26:27]
	v_pk_mul_f32 v[28:29], v[6:7], v[36:37]
	v_pk_mul_f32 v[18:19], v[18:19], v[38:39] op_sel_hi:[1,0]
	v_cvt_pk_bf16_f32 v36, v28, v29
	v_cvt_pk_bf16_f32 v37, v26, v27
	global_store_dwordx2 v[30:31], v[36:37], off offset:512
	v_pk_mul_f32 v[36:37], v[22:23], v[38:39] op_sel_hi:[1,0]
	v_pk_mul_f32 v[22:23], v[24:25], v[38:39] op_sel_hi:[1,0]
	v_pk_mul_f32 v[24:25], v[10:11], v[36:37]
	v_pk_mul_f32 v[22:23], v[12:13], v[22:23]
	v_cvt_pk_bf16_f32 v36, v24, v25
	v_pk_mul_f32 v[20:21], v[20:21], v[38:39] op_sel_hi:[1,0]
	v_cvt_pk_bf16_f32 v37, v22, v23
	global_store_dwordx2 v[30:31], v[36:37], off offset:1024
	v_pk_mul_f32 v[20:21], v[16:17], v[20:21]
	v_pk_mul_f32 v[36:37], v[14:15], v[18:19]
	s_nop 0
	v_cvt_pk_bf16_f32 v18, v36, v37
	v_cvt_pk_bf16_f32 v19, v20, v21
	ds_read_b128 v[38:41], v1
	ds_read_b128 v[54:57], v1 offset:1024
	global_store_dwordx2 v[30:31], v[18:19], off offset:1536
	ds_read_b128 v[78:81], v1 offset:21504
	s_waitcnt lgkmcnt(2)
	v_mul_f32_e32 v39, v35, v39
	v_fmac_f32_e32 v39, v34, v38
	v_mul_f32_e32 v38, v33, v41
	v_fmac_f32_e32 v38, v32, v40
	v_add_f32_e32 v38, v39, v38
	s_waitcnt lgkmcnt(1)
	v_mul_f32_e32 v55, v29, v55
	v_add_f32_e32 v58, 0, v38
	v_fmac_f32_e32 v55, v28, v54
	v_mul_f32_e32 v54, v27, v57
	ds_read_b128 v[38:41], v1 offset:2048
	v_fmac_f32_e32 v54, v26, v56
	v_add_f32_e32 v54, v55, v54
	v_add_f32_e32 v58, v58, v54
	ds_read_b128 v[54:57], v1 offset:3072
	s_waitcnt lgkmcnt(1)
	v_mul_f32_e32 v39, v25, v39
	v_fmac_f32_e32 v39, v24, v38
	v_mul_f32_e32 v38, v23, v41
	v_fmac_f32_e32 v38, v22, v40
	v_add_f32_e32 v38, v39, v38
	s_waitcnt lgkmcnt(0)
	v_mul_f32_e32 v39, v37, v55
	v_mul_f32_e32 v40, v21, v57
	v_fmac_f32_e32 v39, v36, v54
	v_fmac_f32_e32 v40, v20, v56
	v_add_f32_e32 v38, v58, v38
	v_add_f32_e32 v39, v39, v40
	v_add_f32_e32 v54, v38, v39
	ds_bpermute_b32 v55, v66, v54
	ds_read_b128 v[38:41], v1 offset:4096
	v_mul_f32_e32 v77, v27, v81
	v_fmac_f32_e32 v77, v26, v80
	s_waitcnt lgkmcnt(1)
	v_add_f32_e32 v58, v54, v55
	ds_read_b128 v[54:57], v1 offset:5120
	s_waitcnt lgkmcnt(1)
	v_mul_f32_e32 v39, v35, v39
	v_fmac_f32_e32 v39, v34, v38
	v_mul_f32_e32 v38, v33, v41
	v_fmac_f32_e32 v38, v32, v40
	v_add_f32_e32 v38, v39, v38
	s_waitcnt lgkmcnt(0)
	v_mul_f32_e32 v55, v29, v55
	v_add_f32_e32 v60, 0, v38
	v_fmac_f32_e32 v55, v28, v54
	v_mul_f32_e32 v54, v27, v57
	ds_read_b128 v[38:41], v1 offset:6144
	v_fmac_f32_e32 v54, v26, v56
	v_add_f32_e32 v54, v55, v54
	v_add_f32_e32 v60, v60, v54
	ds_read_b128 v[54:57], v1 offset:7168
	s_waitcnt lgkmcnt(1)
	v_mul_f32_e32 v39, v25, v39
	v_fmac_f32_e32 v39, v24, v38
	v_mul_f32_e32 v38, v23, v41
	v_fmac_f32_e32 v38, v22, v40
	v_add_f32_e32 v38, v39, v38
	s_waitcnt lgkmcnt(0)
	v_mul_f32_e32 v39, v37, v55
	v_mul_f32_e32 v40, v21, v57
	ds_bpermute_b32 v59, v67, v58
	v_fmac_f32_e32 v39, v36, v54
	v_fmac_f32_e32 v40, v20, v56
	v_add_f32_e32 v38, v60, v38
	v_add_f32_e32 v39, v39, v40
	v_add_f32_e32 v38, v38, v39
	ds_bpermute_b32 v39, v66, v38
	s_waitcnt lgkmcnt(1)
	v_add_f32_e32 v40, v58, v59
	ds_bpermute_b32 v41, v68, v40
	s_waitcnt lgkmcnt(1)
	v_add_f32_e32 v54, v38, v39
	ds_bpermute_b32 v55, v67, v54
	s_waitcnt lgkmcnt(1)
	v_add_f32_e32 v58, v40, v41
	ds_read_b128 v[38:41], v1 offset:8192
	ds_bpermute_b32 v59, v69, v58
	s_waitcnt lgkmcnt(2)
	v_add_f32_e32 v60, v54, v55
	ds_read_b128 v[54:57], v1 offset:9216
	s_waitcnt lgkmcnt(2)
	v_mul_f32_e32 v39, v35, v39
	v_fmac_f32_e32 v39, v34, v38
	v_mul_f32_e32 v38, v33, v41
	v_fmac_f32_e32 v38, v32, v40
	v_add_f32_e32 v38, v39, v38
	s_waitcnt lgkmcnt(0)
	v_mul_f32_e32 v55, v29, v55
	v_add_f32_e32 v62, 0, v38
	v_fmac_f32_e32 v55, v28, v54
	v_mul_f32_e32 v54, v27, v57
	ds_read_b128 v[38:41], v1 offset:10240
	v_fmac_f32_e32 v54, v26, v56
	v_add_f32_e32 v54, v55, v54
	v_add_f32_e32 v62, v62, v54
	ds_read_b128 v[54:57], v1 offset:11264
	s_waitcnt lgkmcnt(1)
	v_mul_f32_e32 v39, v25, v39
	v_fmac_f32_e32 v39, v24, v38
	v_mul_f32_e32 v38, v23, v41
	v_fmac_f32_e32 v38, v22, v40
	v_add_f32_e32 v38, v39, v38
	s_waitcnt lgkmcnt(0)
	v_mul_f32_e32 v39, v37, v55
	v_mul_f32_e32 v40, v21, v57
	v_fmac_f32_e32 v39, v36, v54
	v_fmac_f32_e32 v40, v20, v56
	v_add_f32_e32 v38, v62, v38
	v_add_f32_e32 v39, v39, v40
	v_add_f32_e32 v38, v38, v39
	ds_bpermute_b32 v61, v68, v60
	ds_bpermute_b32 v39, v66, v38
	v_add_f32_e32 v40, v58, v59
	ds_bpermute_b32 v41, v70, v40
	ds_read_b128 v[54:57], v1 offset:12288
	s_waitcnt lgkmcnt(3)
	v_add_f32_e32 v58, v60, v61
	s_waitcnt lgkmcnt(2)
	v_add_f32_e32 v60, v38, v39
	ds_bpermute_b32 v59, v69, v58
	ds_bpermute_b32 v61, v67, v60
	s_waitcnt lgkmcnt(3)
	v_add_f32_e32 v38, v40, v41
	ds_bpermute_b32 v39, v71, v38
	s_waitcnt lgkmcnt(2)
	v_add_f32_e32 v40, v58, v59
	s_waitcnt lgkmcnt(1)
	v_add_f32_e32 v41, v60, v61
	ds_read_b128 v[58:61], v1 offset:13312
	v_mul_f32_e32 v55, v35, v55
	v_fmac_f32_e32 v55, v34, v54
	v_mul_f32_e32 v54, v33, v57
	v_fmac_f32_e32 v54, v32, v56
	v_add_f32_e32 v54, v55, v54
	s_waitcnt lgkmcnt(0)
	v_mul_f32_e32 v59, v29, v59
	v_add_f32_e32 v63, 0, v54
	v_fmac_f32_e32 v59, v28, v58
	v_mul_f32_e32 v58, v27, v61
	ds_read_b128 v[54:57], v1 offset:14336
	v_fmac_f32_e32 v58, v26, v60
	v_add_f32_e32 v58, v59, v58
	v_add_f32_e32 v63, v63, v58
	ds_read_b128 v[58:61], v1 offset:15360
	s_waitcnt lgkmcnt(1)
	v_mul_f32_e32 v55, v25, v55
	v_fmac_f32_e32 v55, v24, v54
	v_mul_f32_e32 v54, v23, v57
	v_fmac_f32_e32 v54, v22, v56
	v_add_f32_e32 v54, v55, v54
	s_waitcnt lgkmcnt(0)
	v_mul_f32_e32 v59, v37, v59
	v_add_f32_e32 v63, v63, v54
	v_fmac_f32_e32 v59, v36, v58
	v_mul_f32_e32 v58, v21, v61
	ds_read_b128 v[54:57], v1 offset:16384
	v_fmac_f32_e32 v58, v20, v60
	v_add_f32_e32 v58, v59, v58
	v_add_f32_e32 v63, v63, v58
	ds_read_b128 v[58:61], v1 offset:17408
	s_waitcnt lgkmcnt(1)
	v_mul_f32_e32 v55, v35, v55
	v_fmac_f32_e32 v55, v34, v54
	v_mul_f32_e32 v54, v33, v57
	v_fmac_f32_e32 v54, v32, v56
	v_add_f32_e32 v54, v55, v54
	s_waitcnt lgkmcnt(0)
	v_mul_f32_e32 v59, v29, v59
	v_add_f32_e32 v65, 0, v54
	v_fmac_f32_e32 v59, v28, v58
	v_mul_f32_e32 v58, v27, v61
	ds_read_b128 v[54:57], v1 offset:18432
	v_fmac_f32_e32 v58, v26, v60
	v_add_f32_e32 v58, v59, v58
	v_add_f32_e32 v65, v65, v58
	ds_read_b128 v[58:61], v1 offset:19456
	s_waitcnt lgkmcnt(1)
	v_mul_f32_e32 v55, v25, v55
	v_fmac_f32_e32 v55, v24, v54
	v_mul_f32_e32 v54, v23, v57
	v_fmac_f32_e32 v54, v22, v56
	v_add_f32_e32 v54, v55, v54
	s_waitcnt lgkmcnt(0)
	v_mul_f32_e32 v55, v37, v59
	v_mul_f32_e32 v56, v21, v61
	v_fmac_f32_e32 v55, v36, v58
	v_fmac_f32_e32 v56, v20, v60
	v_add_f32_e32 v54, v65, v54
	v_add_f32_e32 v55, v55, v56
	v_add_f32_e32 v54, v54, v55
	ds_bpermute_b32 v64, v66, v63
	ds_bpermute_b32 v55, v66, v54
	ds_bpermute_b32 v62, v68, v41
	ds_bpermute_b32 v56, v70, v40
	s_waitcnt lgkmcnt(3)
	v_add_f32_e32 v57, v63, v64
	s_waitcnt lgkmcnt(2)
	v_add_f32_e32 v54, v54, v55
	ds_bpermute_b32 v58, v67, v57
	ds_bpermute_b32 v55, v67, v54
	s_waitcnt lgkmcnt(3)
	v_add_f32_e32 v41, v41, v62
	ds_bpermute_b32 v59, v69, v41
	s_waitcnt lgkmcnt(3)
	v_add_f32_e32 v40, v40, v56
	s_waitcnt lgkmcnt(2)
	v_add_f32_e32 v57, v57, v58
	s_waitcnt lgkmcnt(1)
	v_add_f32_e32 v54, v54, v55
	ds_bpermute_b32 v58, v68, v57
	ds_bpermute_b32 v55, v68, v54
	s_waitcnt lgkmcnt(2)
	v_add_f32_e32 v41, v41, v59
	ds_read_b128 v[60:63], v1 offset:20480
	s_waitcnt lgkmcnt(2)
	v_add_f32_e32 v56, v57, v58
	s_waitcnt lgkmcnt(1)
	v_add_f32_e32 v54, v54, v55
	ds_bpermute_b32 v57, v69, v56
	ds_bpermute_b32 v59, v69, v54
	s_waitcnt lgkmcnt(2)
	v_mul_f32_e32 v61, v35, v61
	v_fmac_f32_e32 v61, v34, v60
	v_mul_f32_e32 v60, v33, v63
	s_waitcnt lgkmcnt(1)
	v_add_f32_e32 v56, v56, v57
	s_waitcnt lgkmcnt(0)
	v_add_f32_e32 v64, v54, v59
	ds_bpermute_b32 v57, v70, v56
	ds_bpermute_b32 v65, v70, v64
	v_fmac_f32_e32 v60, v32, v62
	v_add_f32_e32 v60, v61, v60
	ds_bpermute_b32 v58, v70, v41
	s_waitcnt lgkmcnt(2)
	v_add_f32_e32 v54, v56, v57
	s_waitcnt lgkmcnt(1)
	v_add_f32_e32 v56, v64, v65
	v_add_f32_e32 v64, 0, v60
	ds_read_b128 v[60:63], v1 offset:22528
	v_mul_f32_e32 v65, v29, v79
	v_fmac_f32_e32 v65, v28, v78
	ds_read_b128 v[78:81], v1 offset:23552
	v_add_f32_e32 v65, v65, v77
	s_waitcnt lgkmcnt(1)
	v_mul_f32_e32 v61, v25, v61
	v_fmac_f32_e32 v61, v24, v60
	v_mul_f32_e32 v60, v23, v63
	v_fmac_f32_e32 v60, v22, v62
	v_add_f32_e32 v64, v64, v65
	v_add_f32_e32 v60, v61, v60
	v_add_f32_e32 v64, v64, v60
	ds_read_b128 v[60:63], v1 offset:24576
	s_waitcnt lgkmcnt(1)
	v_mul_f32_e32 v65, v37, v79
	v_mul_f32_e32 v77, v21, v81
	v_fmac_f32_e32 v65, v36, v78
	v_fmac_f32_e32 v77, v20, v80
	ds_read_b128 v[78:81], v1 offset:25600
	s_waitcnt lgkmcnt(1)
	v_mul_f32_e32 v61, v35, v61
	v_fmac_f32_e32 v61, v34, v60
	v_mul_f32_e32 v60, v33, v63
	v_fmac_f32_e32 v60, v32, v62
	s_waitcnt lgkmcnt(0)
	v_mul_f32_e32 v79, v29, v79
	v_add_f32_e32 v60, v61, v60
	v_fmac_f32_e32 v79, v28, v78
	v_mul_f32_e32 v78, v27, v81
	v_add_f32_e32 v65, v65, v77
	v_add_f32_e32 v77, 0, v60
	ds_read_b128 v[60:63], v1 offset:26624
	v_fmac_f32_e32 v78, v26, v80
	v_add_f32_e32 v78, v79, v78
	v_add_f32_e32 v77, v77, v78
	ds_read_b128 v[78:81], v1 offset:27648
	s_waitcnt lgkmcnt(1)
	v_mul_f32_e32 v61, v25, v61
	v_fmac_f32_e32 v61, v24, v60
	v_mul_f32_e32 v60, v23, v63
	v_fmac_f32_e32 v60, v22, v62
	s_waitcnt lgkmcnt(0)
	v_mul_f32_e32 v79, v37, v79
	v_add_f32_e32 v60, v61, v60
	v_fmac_f32_e32 v79, v36, v78
	v_mul_f32_e32 v78, v21, v81
	v_add_f32_e32 v77, v77, v60
	v_fmac_f32_e32 v78, v20, v80
	ds_read_b128 v[60:63], v1 offset:28672
	v_add_f32_e32 v78, v79, v78
	v_add_f32_e32 v77, v77, v78
	ds_read_b128 v[78:81], v1 offset:29696
	v_add_f32_e32 v64, v64, v65
	s_waitcnt lgkmcnt(1)
	v_mul_f32_e32 v35, v35, v61
	v_mul_f32_e32 v33, v33, v63
	v_fmac_f32_e32 v35, v34, v60
	v_fmac_f32_e32 v33, v32, v62
	v_add_f32_e32 v32, v35, v33
	s_waitcnt lgkmcnt(0)
	v_mul_f32_e32 v29, v29, v79
	v_mul_f32_e32 v27, v27, v81
	v_add_f32_e32 v60, 0, v32
	v_fmac_f32_e32 v29, v28, v78
	ds_read_b128 v[32:35], v1 offset:30720
	v_fmac_f32_e32 v27, v26, v80
	v_add_f32_e32 v26, v29, v27
	v_add_f32_e32 v60, v60, v26
	ds_read_b128 v[26:29], v1 offset:31744
	s_waitcnt lgkmcnt(1)
	v_mul_f32_e32 v25, v25, v33
	v_mul_f32_e32 v23, v23, v35
	v_fmac_f32_e32 v25, v24, v32
	v_fmac_f32_e32 v23, v22, v34
	v_add_f32_e32 v22, v25, v23
	s_waitcnt lgkmcnt(0)
	v_mul_f32_e32 v23, v37, v27
	v_mul_f32_e32 v21, v21, v29
	v_fmac_f32_e32 v23, v36, v26
	v_fmac_f32_e32 v21, v20, v28
	v_add_f32_e32 v22, v60, v22
	v_add_f32_e32 v20, v23, v21
	v_add_f32_e32 v20, v22, v20
	ds_bpermute_b32 v65, v66, v64
	ds_bpermute_b32 v82, v66, v77
	ds_bpermute_b32 v21, v66, v20
	v_add_f32_e32 v41, v41, v58
	ds_bpermute_b32 v55, v71, v40
	s_waitcnt lgkmcnt(3)
	v_add_f32_e32 v22, v64, v65
	s_waitcnt lgkmcnt(2)
	v_add_f32_e32 v24, v77, v82
	s_waitcnt lgkmcnt(1)
	v_add_f32_e32 v20, v20, v21
	ds_bpermute_b32 v23, v67, v22
	ds_bpermute_b32 v25, v67, v24
	ds_bpermute_b32 v21, v67, v20
	ds_bpermute_b32 v58, v71, v41
	ds_bpermute_b32 v59, v71, v54
	s_waitcnt lgkmcnt(4)
	v_add_f32_e32 v22, v22, v23
	s_waitcnt lgkmcnt(3)
	v_add_f32_e32 v24, v24, v25
	s_waitcnt lgkmcnt(2)
	v_add_f32_e32 v20, v20, v21
	ds_bpermute_b32 v23, v68, v22
	ds_bpermute_b32 v25, v68, v24
	ds_bpermute_b32 v21, v68, v20
	ds_bpermute_b32 v57, v71, v56
	s_waitcnt lgkmcnt(3)
	v_add_f32_e32 v22, v22, v23
	s_waitcnt lgkmcnt(2)
	v_add_f32_e32 v24, v24, v25
	s_waitcnt lgkmcnt(1)
	v_add_f32_e32 v20, v20, v21
	ds_bpermute_b32 v23, v69, v22
	ds_bpermute_b32 v25, v69, v24
	ds_bpermute_b32 v21, v69, v20
	s_waitcnt lgkmcnt(2)
	v_add_f32_e32 v22, v22, v23
	s_waitcnt lgkmcnt(1)
	v_add_f32_e32 v26, v24, v25
	s_waitcnt lgkmcnt(0)
	v_add_f32_e32 v20, v20, v21
	ds_bpermute_b32 v23, v70, v22
	ds_bpermute_b32 v27, v70, v26
	ds_bpermute_b32 v21, v70, v20
	s_waitcnt lgkmcnt(2)
	v_add_f32_e32 v24, v22, v23
	s_waitcnt lgkmcnt(1)
	v_add_f32_e32 v22, v26, v27
	s_waitcnt lgkmcnt(0)
	v_add_f32_e32 v20, v20, v21
	ds_bpermute_b32 v25, v71, v24
	ds_bpermute_b32 v23, v71, v22
	ds_bpermute_b32 v21, v71, v20
	s_and_b64 exec, exec, s[68:69]
	s_cbranch_execz .Lp0_nob
	v_lshl_add_u64 v[18:19], s[74:75], 0, v[46:47]
	v_add_f32_e32 v27, v38, v39
	v_add_co_u32_e32 v18, vcc, 0x26a8000, v18
	s_nop 0
	v_addc_co_u32_e32 v19, vcc, 0, v19, vcc
	s_waitcnt lgkmcnt(2)
	v_add_f32_e32 v24, v24, v25
	s_waitcnt lgkmcnt(1)
	v_add_f32_e32 v22, v22, v23
	s_waitcnt lgkmcnt(0)
	v_add_f32_e32 v20, v20, v21
	v_add_f32_e32 v28, v40, v55
	v_add_f32_e32 v29, v41, v58
	v_add_f32_e32 v30, v54, v59
	v_cndmask_b32_e64 v27, v27, v28, s[18:19]
	v_cndmask_b32_e64 v27, v27, v29, s[20:21]
	v_cndmask_b32_e64 v27, v27, v30, s[22:23]
	v_add_f32_e32 v26, v110, v27
	v_add_co_u32_e32 v18, vcc, v112, v18
	s_nop 1
	v_addc_co_u32_e32 v19, vcc, 0, v19, vcc
	global_store_dword v[18:19], v26, off
	v_add_f32_e32 v27, v56, v57
	v_cndmask_b32_e64 v27, v27, v24, s[18:19]
	v_cndmask_b32_e64 v27, v27, v22, s[20:21]
	v_cndmask_b32_e64 v27, v27, v20, s[22:23]
	v_add_f32_e32 v26, v111, v27
	s_mov_b64 exec, 0xff
	s_nop 4
	v_mov_b32_dpp v26, v113 row_shr:4 row_mask:0xf bank_mask:0x2
	v_mov_b32_dpp v18, v114 row_shr:4 row_mask:0xf bank_mask:0x2
	v_mov_b32_dpp v19, v115 row_shr:4 row_mask:0xf bank_mask:0x2
	v_mul_f32_e64 v27, |v26|, s30
	v_fma_f32 v28, |v26|, s30, -v27
	v_rndne_f32_e32 v29, v27
	v_fma_f32 v28, |v26|, s31, v28
	v_sub_f32_e32 v27, v27, v29
	v_add_f32_e32 v27, v27, v28
	v_cvt_i32_f32_e32 v29, v29
	v_exp_f32_e32 v27, v27
	v_cmp_ngt_f32_e64 vcc, |v26|, s34
	v_min_f32_e32 v28, 0, v26
	v_ldexp_f32 v27, v27, v29
	v_cndmask_b32_e32 v27, 0, v27, vcc
	v_cmp_nlt_f32_e64 vcc, |v26|, s35
	s_nop 1
	v_cndmask_b32_e32 v29, v76, v27, vcc
	v_add_f32_e32 v30, 1.0, v29
	v_add_f32_e32 v31, -1.0, v30
	v_frexp_mant_f32_e32 v32, v30
	v_cvt_f64_f32_e32 v[26:27], v30
	v_sub_f32_e32 v33, v31, v30
	v_frexp_exp_i32_f64_e32 v26, v[26:27]
	v_cmp_gt_f32_e32 vcc, s65, v32
	v_sub_f32_e32 v31, v29, v31
	v_add_f32_e32 v27, 1.0, v33
	v_subbrev_co_u32_e32 v26, vcc, 0, v26, vcc
	v_add_f32_e32 v27, v31, v27
	v_sub_u32_e32 v31, 0, v26
	v_cvt_f32_i32_e32 v26, v26
	v_ldexp_f32 v30, v30, v31
	v_ldexp_f32 v27, v27, v31
	v_add_f32_e32 v31, -1.0, v30
	v_add_f32_e32 v32, 1.0, v30
	v_add_f32_e32 v33, 1.0, v31
	v_add_f32_e32 v34, -1.0, v32
	v_sub_f32_e32 v33, v30, v33
	v_sub_f32_e32 v30, v30, v34
	v_mul_f32_e32 v34, 0x3f317218, v26
	v_add_f32_e32 v33, v27, v33
	v_add_f32_e32 v27, v27, v30
	v_fma_f32 v30, v26, s66, -v34
	v_add_f32_e32 v35, v31, v33
	v_add_f32_e32 v36, v32, v27
	v_fmac_f32_e32 v30, 0xb102e308, v26
	v_sub_f32_e32 v26, v31, v35
	v_sub_f32_e32 v31, v32, v36
	v_rcp_f32_e32 v32, v36
	v_add_f32_e32 v37, v34, v30
	v_add_f32_e32 v27, v27, v31
	v_sub_f32_e32 v31, v37, v34
	v_sub_f32_e32 v30, v30, v31
	v_mul_f32_e32 v31, v35, v32
	v_add_f32_e32 v26, v33, v26
	v_mul_f32_e32 v33, v36, v31
	v_fma_f32 v34, v31, v36, -v33
	v_fmac_f32_e32 v34, v31, v27
	v_add_f32_e32 v38, v33, v34
	v_sub_f32_e32 v39, v35, v38
	v_sub_f32_e32 v33, v38, v33
	v_sub_f32_e32 v35, v35, v39
	v_sub_f32_e32 v33, v33, v34
	v_sub_f32_e32 v34, v35, v38
	v_add_f32_e32 v26, v26, v34
	v_add_f32_e32 v26, v33, v26
	v_add_f32_e32 v33, v39, v26
	v_mul_f32_e32 v34, v32, v33
	v_sub_f32_e32 v35, v39, v33
	v_mul_f32_e32 v38, v36, v34
	v_add_f32_e32 v26, v26, v35
	v_add_f32_e32 v35, v31, v34
	v_fma_f32 v36, v34, v36, -v38
	v_sub_f32_e32 v31, v35, v31
	v_fmac_f32_e32 v36, v34, v27
	v_sub_f32_e32 v27, v34, v31
	v_add_f32_e32 v31, v38, v36
	v_sub_f32_e32 v34, v31, v38
	v_sub_f32_e32 v38, v33, v31
	v_sub_f32_e32 v33, v33, v38
	v_sub_f32_e32 v31, v33, v31
	v_sub_f32_e32 v34, v34, v36
	v_add_f32_e32 v26, v26, v31
	v_add_f32_e32 v26, v34, v26
	v_add_f32_e32 v26, v38, v26
	v_mul_f32_e32 v26, v32, v26
	v_add_f32_e32 v26, v27, v26
	v_add_f32_e32 v27, v35, v26
	v_mul_f32_e32 v31, v27, v27
	v_fmamk_f32 v34, v31, 0x3e9b6dac, v75
	v_sub_f32_e32 v32, v27, v35
	v_ldexp_f32 v33, v27, 1
	v_mul_f32_e32 v27, v27, v31
	v_fmaak_f32 v31, v31, v34, 0x3f2aaada
	v_mul_f32_e32 v27, v27, v31
	v_add_f32_e32 v31, v33, v27
	v_sub_f32_e32 v26, v26, v32
	v_sub_f32_e32 v32, v31, v33
	v_ldexp_f32 v26, v26, 1
	v_sub_f32_e32 v27, v27, v32
	v_add_f32_e32 v26, v26, v27
	v_add_f32_e32 v27, v31, v26
	v_sub_f32_e32 v31, v27, v31
	v_add_f32_e32 v32, v37, v27
	v_sub_f32_e32 v26, v26, v31
	v_sub_f32_e32 v31, v32, v37
	v_sub_f32_e32 v33, v32, v31
	v_sub_f32_e32 v27, v27, v31
	v_add_f32_e32 v31, v30, v26
	v_sub_f32_e32 v33, v37, v33
	v_sub_f32_e32 v34, v31, v30
	v_add_f32_e32 v27, v27, v33
	v_sub_f32_e32 v33, v31, v34
	v_sub_f32_e32 v26, v26, v34
	v_sub_f32_e32 v30, v30, v33
	v_add_f32_e32 v27, v31, v27
	v_add_f32_e32 v26, v26, v30
	v_add_f32_e32 v30, v32, v27
	v_sub_f32_e32 v31, v30, v32
	v_sub_f32_e32 v27, v27, v31
	v_add_f32_e32 v26, v26, v27
	v_add_f32_e32 v26, v30, v26
	v_cmp_neq_f32_e32 vcc, s64, v29
	s_nop 1
	v_cndmask_b32_e32 v26, v76, v26, vcc
	v_cmp_lt_f32_e64 vcc, |v29|, s67
	s_nop 1
	v_cndmask_b32_e32 v26, v26, v29, vcc
	v_sub_f32_e32 v26, v28, v26
	global_store_dword v[18:19], v26, off offset:16
	s_branch .LBB0_25
